# P.V fragment reads 3 pairs ahead in attention; QK-norm epilogue gain loads batched
# speedup vs baseline: 1.0415x; 1.0068x over previous
;     __device__ __forceinline__ void operator()(const AccT& acc, const Unit& u, int wr, int wc, int fr, int fq) const {
;         const int kind = (u.pn + pn_off) >> 3, tile = (u.pn + pn_off) & 7;
;         bf16_t* base = Q + (size_t)kind * ((WS_K - WS_Q) / 2); if (kind == 2) base = Z;
;         const float* g = gq; if (kind == 1) g = gk; const float gs = kind == 0 ? C2 : 1.f;
;         f32x4 gv[2][2];
; #pragma unroll
;         for (int bj = 0; bj < 2; ++bj)
; #pragma unroll
;             for (int n = 0; n < 2; ++n) gv[bj][n] = (kind < 2) ? *(const f32x4*)(g + 32 * bj + 8 * fq + 4 * n) * gs : (f32x4){1.f, 1.f, 1.f, 1.f};
;         const int row0 = u.pm * 256 + wr * 64 + fr;
; #pragma unroll
;         for (int ai = 0; ai < 2; ++ai)
; #pragma unroll
;             for (int m = 0; m < 4; ++m) {
;                 const int row = row0 + ai * 128 + m * 16; float rs = 1.f;
;                 if (kind < 2) { float ss = 0.f;
; #pragma unroll
;                     for (int bj = 0; bj < 2; ++bj)
; #pragma unroll
;                         for (int n = 0; n < 2; ++n) { const f32x4 v = acc[ai][bj][m][n]; ss += (v[0] * v[0] + v[1] * v[1]) + (v[2] * v[2] + v[3] * v[3]); }
;                     ss += __shfl_xor(ss, 16); ss += __shfl_xor(ss, 32); rs = rsqrtf(ss * (1.f / 64.f) + EPS); }
.LBB0_119:
	s_ashr_i32 s66, s64, 3
	s_cmp_eq_u32 s66, 1
	s_cselect_b32 s7, s21, s19
	s_cselect_b32 s6, s20, s18
	s_cmp_lt_u32 s64, 8
	s_cselect_b64 vcc, -1, 0
	v_cndmask_b32_e32 v164, 1.0, v179, vcc
	v_mov_b32_e32 v148, 1.0
	v_mov_b32_e32 v149, 1.0
	v_mov_b32_e32 v150, 1.0
	v_mov_b32_e32 v151, 1.0
	v_mov_b32_e32 v152, 1.0
	v_mov_b32_e32 v153, 1.0
	v_mov_b32_e32 v154, 1.0
	v_mov_b32_e32 v155, 1.0
	v_mov_b32_e32 v156, 1.0
	v_mov_b32_e32 v157, 1.0
	v_mov_b32_e32 v158, 1.0
	v_mov_b32_e32 v159, 1.0
	v_mov_b32_e32 v160, 1.0
	v_mov_b32_e32 v161, 1.0
	v_mov_b32_e32 v162, 1.0
	v_mov_b32_e32 v163, 1.0
	v_mov_b32_e32 v165, v164
	v_lshl_add_u64 v[166:167], s[6:7], 0, v[136:137]
	s_cmp_lt_i32 s66, 2
	s_cselect_b64 s[70:71], -1, 0
	s_cbranch_scc0 .Lqk_nog
	global_load_dwordx4 v[150:153], v[166:167], off
	global_load_dwordx4 v[184:187], v[166:167], off offset:16
	global_load_dwordx4 v[158:161], v[166:167], off offset:128
	global_load_dwordx4 v[188:191], v[166:167], off offset:144
	s_waitcnt vmcnt(0)
	v_pk_mul_f32 v[150:151], v[164:165], v[150:151]
	v_pk_mul_f32 v[152:153], v[164:165], v[152:153]
	v_pk_mul_f32 v[148:149], v[164:165], v[184:185]
	v_pk_mul_f32 v[156:157], v[164:165], v[186:187]
	v_pk_mul_f32 v[158:159], v[164:165], v[158:159]
	v_pk_mul_f32 v[160:161], v[164:165], v[160:161]
	v_pk_mul_f32 v[154:155], v[164:165], v[188:189]
	v_pk_mul_f32 v[162:163], v[164:165], v[190:191]
.Lqk_nog:
	s_andn2_b64 s[6:7], exec, s[70:71]
	v_mov_b32_e32 v168, 1.0
	s_and_b64 vcc, exec, s[6:7]
	v_mov_b32_e32 v170, 1.0
	s_cbranch_vccnz .LBB0_129
	v_pk_mul_f32 v[164:165], v[126:127], v[126:127]
	v_pk_mul_f32 v[166:167], v[124:125], v[124:125]
	v_mul_f32_e32 v170, v112, v112
	v_pk_mov_b32 v[180:181], v[166:167], v[164:165] op_sel:[1,0]
	v_mov_b32_e32 v167, v165
	v_pk_add_f32 v[164:165], v[180:181], v[166:167]
	v_pk_mul_f32 v[166:167], v[122:123], v[122:123]
	v_pk_mul_f32 v[180:181], v[120:121], v[120:121]
	v_pk_add_f32 v[164:165], v[164:165], v[164:165] op_sel:[0,1] op_sel_hi:[1,0]
	v_pk_mov_b32 v[182:183], v[180:181], v[166:167] op_sel:[1,0]
	v_mov_b32_e32 v181, v167
	v_pk_add_f32 v[166:167], v[182:183], v[180:181]
	v_mul_f32_e32 v180, v113, v113
	v_pk_add_f32 v[166:167], v[166:167], v[166:167] op_sel:[0,1] op_sel_hi:[1,0]
	v_mov_b32_e32 v165, v170
	v_mov_b32_e32 v167, v180
	v_pk_add_f32 v[164:165], v[164:165], v[166:167]
	v_mul_f32_e32 v166, v117, v117
	v_mul_f32_e32 v181, v114, v114
	v_pk_fma_f32 v[166:167], v[116:117], v[116:117], v[166:167] op_sel_hi:[1,1,0]
	v_mul_f32_e32 v170, v119, v119
	v_mul_f32_e32 v182, v115, v115
	v_mov_b32_e32 v167, v181
	v_pk_fma_f32 v[180:181], v[118:119], v[118:119], v[170:171] op_sel_hi:[1,1,0]
	s_nop 0
	v_mov_b32_e32 v181, v182
	v_pk_add_f32 v[166:167], v[166:167], v[180:181]
	s_nop 0
	v_pk_add_f32 v[164:165], v[164:165], v[166:167]
	s_nop 0
	v_add_f32_e32 v164, v164, v165
	ds_bpermute_b32 v165, v173, v164
	s_waitcnt lgkmcnt(0)
	v_add_f32_e32 v164, v164, v165
	ds_bpermute_b32 v165, v174, v164
	s_waitcnt lgkmcnt(0)
	v_add_f32_e32 v164, v164, v165
	v_fmamk_f32 v164, v164, 0x3c800000, v178
	v_mul_f32_e32 v165, 0x4b800000, v164
	v_cmp_gt_f32_e32 vcc, s81, v164
	s_nop 1
	v_cndmask_b32_e32 v164, v164, v165, vcc
	v_rsq_f32_e32 v164, v164
	s_nop 0
	v_mul_f32_e32 v165, 0x45800000, v164
	v_cndmask_b32_e32 v170, v164, v165, vcc

; #define LAS __attribute__((address_space(3)))
; __device__ __forceinline__ unsigned cvtpk_s(float lo, float hi) { f32x2_t v = {lo, hi}; bf16x2_t b = __builtin_convertvector(v, bf16x2_t); return __builtin_bit_cast(unsigned, b); }
; template <int HF> ...
;     ...
;         float ls = 0.f;
; #pragma unroll
;         for (int r = 0; r < 16; ++r) { p[r] = __builtin_amdgcn_exp2f(p[r]); ls += p[r]; }
;         lsum[sub] += ls;
;         pw[sub][0] = (u32x4){cvtpk_s(p[0], p[1]), cvtpk_s(p[2], p[3]), cvtpk_s(p[4], p[5]), cvtpk_s(p[6], p[7])};
;         pw[sub][1] = (u32x4){cvtpk_s(p[8], p[9]), cvtpk_s(p[10], p[11]), cvtpk_s(p[12], p[13]), cvtpk_s(p[14], p[15])};
;         __builtin_amdgcn_sched_barrier(0);
;         if (sub == 0 && stage) {
;             if (HF == 0) { *(LAS u32x4*)sdst = st0; *(LAS u32x4*)(sdst + 32 * KROW) = st1; }
;             else { *(LAS u32x2*)sdst = (u32x2){st0.x, st0.y}; *(LAS u32x2*)(sdst + 8) = (u32x2){st0.z, st0.w}; *(LAS u32x2*)(sdst + 64 * VROW) = (u32x2){st1.x, st1.y}; *(LAS u32x2*)(sdst + 64 * VROW + 8) = (u32x2){st1.z, st1.w}; }
;             __builtin_amdgcn_sched_barrier(0);
;         }
;     }
;     ...
;     bf16x8 vcur = AT_VFRAG(0);
;     __builtin_amdgcn_s_setprio(1);
; #pragma unroll
;     for (int idx = 0; idx < 8; ++idx) {
;         bf16x8 vnext = vcur;
;         if (idx + 1 < 8) vnext = AT_VFRAG(idx + 1);
;         const int kk = idx >> 2, d = idx & 3;
;         o[0][d] = __builtin_amdgcn_mfma_f32_32x32x16_bf16(vcur, __builtin_bit_cast(bf16x8, pw[0][kk]), o[0][d], 0, 0, 0);
;         o[1][d] = __builtin_amdgcn_mfma_f32_32x32x16_bf16(vcur, __builtin_bit_cast(bf16x8, pw[1][kk]), o[1][d], 0, 0, 0);
;         __builtin_amdgcn_sched_barrier(0);
;         vcur = vnext;
;     }
.LBB0_258:
	v_exp_f32_e32 v227, v144
	v_exp_f32_e32 v248, v145
	v_exp_f32_e32 v249, v146
	v_exp_f32_e32 v250, v147
	v_add_f32_e32 v144, 0, v227
	v_exp_f32_e32 v148, v148
	v_add_f32_e32 v144, v248, v144
	v_exp_f32_e32 v149, v149
	v_add_f32_e32 v144, v249, v144
	v_exp_f32_e32 v150, v150
	v_add_f32_e32 v144, v250, v144
	v_exp_f32_e32 v151, v151
	v_add_f32_e32 v144, v148, v144
	v_exp_f32_e32 v152, v152
	v_add_f32_e32 v144, v149, v144
	v_exp_f32_e32 v153, v153
	v_add_f32_e32 v144, v150, v144
	v_exp_f32_e32 v145, v154
	v_add_f32_e32 v144, v151, v144
	v_exp_f32_e32 v154, v155
	v_add_f32_e32 v144, v152, v144
	v_exp_f32_e32 v146, v156
	v_add_f32_e32 v144, v153, v144
	v_exp_f32_e32 v155, v157
	v_add_f32_e32 v144, v145, v144
	v_exp_f32_e32 v147, v158
	v_add_f32_e32 v144, v154, v144
	v_exp_f32_e32 v156, v159
	v_add_f32_e32 v144, v146, v144
	v_exp_f32_e32 v128, v128
	v_add_f32_e32 v144, v155, v144
	v_exp_f32_e32 v129, v129
	v_add_f32_e32 v144, v147, v144
	v_exp_f32_e32 v130, v130
	v_add_f32_e32 v144, v156, v144
	v_exp_f32_e32 v131, v131
	v_add_f32_e32 v224, v224, v144
	v_cvt_pk_bf16_f32 v144, v152, v153
	v_add_f32_e32 v152, 0, v128
	v_exp_f32_e32 v132, v132
	v_add_f32_e32 v152, v129, v152
	v_exp_f32_e32 v133, v133
	v_add_f32_e32 v152, v130, v152
	v_exp_f32_e32 v134, v134
	v_add_f32_e32 v152, v131, v152
	v_exp_f32_e32 v135, v135
	v_add_f32_e32 v152, v132, v152
	v_exp_f32_e32 v136, v136
	v_add_f32_e32 v152, v133, v152
	v_exp_f32_e32 v137, v137
	v_add_f32_e32 v152, v134, v152
	v_exp_f32_e32 v138, v138
	v_add_f32_e32 v152, v135, v152
	v_exp_f32_e32 v139, v139
	v_add_f32_e32 v152, v136, v152
	v_exp_f32_e32 v140, v140
	v_add_f32_e32 v152, v137, v152
	v_exp_f32_e32 v141, v141
	v_add_f32_e32 v152, v138, v152
	v_exp_f32_e32 v142, v142
	v_add_f32_e32 v152, v139, v152
	v_exp_f32_e32 v143, v143
	v_add_f32_e32 v152, v140, v152
	v_add_f32_e32 v152, v141, v152
	v_add_f32_e32 v152, v142, v152
	v_add_f32_e32 v152, v143, v152
	v_add_f32_e32 v225, v225, v152
	v_cvt_pk_bf16_f32 v147, v147, v156
	v_cvt_pk_bf16_f32 v146, v146, v155
	v_cvt_pk_bf16_f32 v145, v145, v154
	v_cvt_pk_bf16_f32 v151, v150, v151
	v_cvt_pk_bf16_f32 v150, v148, v149
	v_cvt_pk_bf16_f32 v149, v249, v250
	v_cvt_pk_bf16_f32 v148, v227, v248
	v_cvt_pk_bf16_f32 v128, v128, v129
	v_cvt_pk_bf16_f32 v129, v130, v131
	v_cvt_pk_bf16_f32 v130, v132, v133
	v_cvt_pk_bf16_f32 v131, v134, v135
	v_cvt_pk_bf16_f32 v132, v136, v137
	v_cvt_pk_bf16_f32 v133, v138, v139
	v_cvt_pk_bf16_f32 v134, v140, v141
	v_cvt_pk_bf16_f32 v135, v142, v143
	v_add_u32_e32 v152, s91, v236
	v_add_u32_e32 v153, 0x8800, v152
	v_add_u32_e32 v154, 0x9800, v152
	v_add_u32_e32 v155, 0xa800, v152
	v_add_u32_e32 v156, 0xb800, v152
	ds_read2_b64 v[136:139], v153 offset0:0 offset1:2
	ds_read2_b64 v[140:143], v154 offset0:32 offset1:34
	ds_read2_b64 v[248:251], v155 offset0:64 offset1:66
	s_setprio 1
	s_waitcnt lgkmcnt(2)
	v_mfma_f32_32x32x16_bf16 v[64:79], v[136:139], v[148:151], v[64:79]
	ds_read2_b64 v[252:255], v156 offset0:96 offset1:98
	v_mfma_f32_32x32x16_bf16 v[112:127], v[136:139], v[128:131], v[112:127]
	s_waitcnt lgkmcnt(2)
	v_mfma_f32_32x32x16_bf16 v[48:63], v[140:143], v[148:151], v[48:63]
	ds_read2_b64 v[136:139], v153 offset0:4 offset1:6
	v_mfma_f32_32x32x16_bf16 v[96:111], v[140:143], v[128:131], v[96:111]
	s_waitcnt lgkmcnt(2)
	v_mfma_f32_32x32x16_bf16 v[16:31], v[248:251], v[148:151], v[16:31]
	ds_read2_b64 v[140:143], v154 offset0:36 offset1:38
	v_mfma_f32_32x32x16_bf16 v[80:95], v[248:251], v[128:131], v[80:95]
	s_waitcnt lgkmcnt(2)
	v_mfma_f32_32x32x16_bf16 v[0:15], v[252:255], v[148:151], v[0:15]
	ds_read2_b64 v[248:251], v155 offset0:68 offset1:70
	v_mfma_f32_32x32x16_bf16 v[32:47], v[252:255], v[128:131], v[32:47]
	s_waitcnt lgkmcnt(2)
	v_mfma_f32_32x32x16_bf16 v[64:79], v[136:139], v[144:147], v[64:79]
	ds_read2_b64 v[252:255], v156 offset0:100 offset1:102
	v_mfma_f32_32x32x16_bf16 v[112:127], v[136:139], v[132:135], v[112:127]
	s_waitcnt lgkmcnt(2)
	v_mfma_f32_32x32x16_bf16 v[48:63], v[140:143], v[144:147], v[48:63]
	v_mfma_f32_32x32x16_bf16 v[96:111], v[140:143], v[132:135], v[96:111]
	s_waitcnt lgkmcnt(1)
	v_mfma_f32_32x32x16_bf16 v[16:31], v[248:251], v[144:147], v[16:31]
	v_mfma_f32_32x32x16_bf16 v[80:95], v[248:251], v[132:135], v[80:95]
	s_waitcnt lgkmcnt(0)
	v_mfma_f32_32x32x16_bf16 v[0:15], v[252:255], v[144:147], v[0:15]
	v_mfma_f32_32x32x16_bf16 v[32:47], v[252:255], v[132:135], v[32:47]
	s_setprio 0

; #define LAS __attribute__((address_space(3)))
; __device__ __forceinline__ unsigned cvtpk_s(float lo, float hi) { f32x2_t v = {lo, hi}; bf16x2_t b = __builtin_convertvector(v, bf16x2_t); return __builtin_bit_cast(unsigned, b); }
; template <int HF> ...
;     ...
;         float ls = 0.f;
; #pragma unroll
;         for (int r = 0; r < 16; ++r) { p[r] = __builtin_amdgcn_exp2f(p[r]); ls += p[r]; }
;         lsum[sub] += ls;
;         pw[sub][0] = (u32x4){cvtpk_s(p[0], p[1]), cvtpk_s(p[2], p[3]), cvtpk_s(p[4], p[5]), cvtpk_s(p[6], p[7])};
;         pw[sub][1] = (u32x4){cvtpk_s(p[8], p[9]), cvtpk_s(p[10], p[11]), cvtpk_s(p[12], p[13]), cvtpk_s(p[14], p[15])};
;         __builtin_amdgcn_sched_barrier(0);
;         if (sub == 0 && stage) {
;             if (HF == 0) { *(LAS u32x4*)sdst = st0; *(LAS u32x4*)(sdst + 32 * KROW) = st1; }
;             else { *(LAS u32x2*)sdst = (u32x2){st0.x, st0.y}; *(LAS u32x2*)(sdst + 8) = (u32x2){st0.z, st0.w}; *(LAS u32x2*)(sdst + 64 * VROW) = (u32x2){st1.x, st1.y}; *(LAS u32x2*)(sdst + 64 * VROW + 8) = (u32x2){st1.z, st1.w}; }
;             __builtin_amdgcn_sched_barrier(0);
;         }
;     }
;     ...
;     bf16x8 vcur = AT_VFRAG(0);
;     __builtin_amdgcn_s_setprio(1);
; #pragma unroll
;     for (int idx = 0; idx < 8; ++idx) {
;         bf16x8 vnext = vcur;
;         if (idx + 1 < 8) vnext = AT_VFRAG(idx + 1);
;         const int kk = idx >> 2, d = idx & 3;
;         o[0][d] = __builtin_amdgcn_mfma_f32_32x32x16_bf16(vcur, __builtin_bit_cast(bf16x8, pw[0][kk]), o[0][d], 0, 0, 0);
;         o[1][d] = __builtin_amdgcn_mfma_f32_32x32x16_bf16(vcur, __builtin_bit_cast(bf16x8, pw[1][kk]), o[1][d], 0, 0, 0);
;         __builtin_amdgcn_sched_barrier(0);
;         vcur = vnext;
;     }
.LBB0_272:
	v_exp_f32_e32 v227, v144
	v_exp_f32_e32 v247, v145
	v_exp_f32_e32 v248, v146
	v_exp_f32_e32 v249, v147
	v_add_f32_e32 v144, 0, v227
	v_exp_f32_e32 v148, v148
	v_add_f32_e32 v144, v247, v144
	v_exp_f32_e32 v149, v149
	v_add_f32_e32 v144, v248, v144
	v_exp_f32_e32 v150, v150
	v_add_f32_e32 v144, v249, v144
	v_exp_f32_e32 v151, v151
	v_add_f32_e32 v144, v148, v144
	v_exp_f32_e32 v152, v152
	v_add_f32_e32 v144, v149, v144
	v_exp_f32_e32 v153, v153
	v_add_f32_e32 v144, v150, v144
	v_exp_f32_e32 v145, v154
	v_add_f32_e32 v144, v151, v144
	v_exp_f32_e32 v154, v155
	v_add_f32_e32 v144, v152, v144
	v_exp_f32_e32 v146, v156
	v_add_f32_e32 v144, v153, v144
	v_exp_f32_e32 v155, v157
	v_add_f32_e32 v144, v145, v144
	v_exp_f32_e32 v147, v158
	v_add_f32_e32 v144, v154, v144
	v_exp_f32_e32 v156, v159
	v_add_f32_e32 v144, v146, v144
	v_exp_f32_e32 v128, v128
	v_add_f32_e32 v144, v155, v144
	v_exp_f32_e32 v129, v129
	v_add_f32_e32 v144, v147, v144
	v_exp_f32_e32 v130, v130
	v_add_f32_e32 v144, v156, v144
	v_exp_f32_e32 v131, v131
	v_add_f32_e32 v224, v224, v144
	v_cvt_pk_bf16_f32 v144, v152, v153
	v_add_f32_e32 v152, 0, v128
	v_exp_f32_e32 v132, v132
	v_add_f32_e32 v152, v129, v152
	v_exp_f32_e32 v133, v133
	v_add_f32_e32 v152, v130, v152
	v_exp_f32_e32 v134, v134
	v_add_f32_e32 v152, v131, v152
	v_exp_f32_e32 v135, v135
	v_add_f32_e32 v152, v132, v152
	v_exp_f32_e32 v136, v136
	v_add_f32_e32 v152, v133, v152
	v_exp_f32_e32 v137, v137
	v_add_f32_e32 v152, v134, v152
	v_exp_f32_e32 v138, v138
	v_add_f32_e32 v152, v135, v152
	v_exp_f32_e32 v139, v139
	v_add_f32_e32 v152, v136, v152
	v_exp_f32_e32 v140, v140
	v_add_f32_e32 v152, v137, v152
	v_exp_f32_e32 v141, v141
	v_add_f32_e32 v152, v138, v152
	v_exp_f32_e32 v142, v142
	v_add_f32_e32 v152, v139, v152
	v_exp_f32_e32 v143, v143
	v_add_f32_e32 v152, v140, v152
	v_add_f32_e32 v152, v141, v152
	v_add_f32_e32 v152, v142, v152
	v_add_f32_e32 v152, v143, v152
	v_add_f32_e32 v225, v225, v152
	v_cvt_pk_bf16_f32 v147, v147, v156
	v_cvt_pk_bf16_f32 v146, v146, v155
	v_cvt_pk_bf16_f32 v145, v145, v154
	v_cvt_pk_bf16_f32 v151, v150, v151
	v_cvt_pk_bf16_f32 v150, v148, v149
	v_cvt_pk_bf16_f32 v149, v248, v249
	v_cvt_pk_bf16_f32 v148, v227, v247
	v_cvt_pk_bf16_f32 v128, v128, v129
	v_cvt_pk_bf16_f32 v129, v130, v131
	v_cvt_pk_bf16_f32 v130, v132, v133
	v_cvt_pk_bf16_f32 v131, v134, v135
	v_cvt_pk_bf16_f32 v132, v136, v137
	v_cvt_pk_bf16_f32 v133, v138, v139
	v_cvt_pk_bf16_f32 v134, v140, v141
	v_cvt_pk_bf16_f32 v135, v142, v143
	v_add_u32_e32 v152, s91, v236
	v_add_u32_e32 v153, 0x8800, v152
	v_add_u32_e32 v154, 0x9800, v152
	v_add_u32_e32 v155, 0xa800, v152
	v_add_u32_e32 v156, 0xb800, v152
	ds_read2_b64 v[136:139], v153 offset0:8 offset1:10
	ds_read2_b64 v[140:143], v154 offset0:40 offset1:42
	ds_read2_b64 v[248:251], v155 offset0:72 offset1:74
	s_setprio 1
	s_waitcnt lgkmcnt(2)
	v_mfma_f32_32x32x16_bf16 v[64:79], v[136:139], v[148:151], v[64:79]
	ds_read2_b64 v[252:255], v156 offset0:104 offset1:106
	v_mfma_f32_32x32x16_bf16 v[112:127], v[136:139], v[128:131], v[112:127]
	s_waitcnt lgkmcnt(2)
	v_mfma_f32_32x32x16_bf16 v[48:63], v[140:143], v[148:151], v[48:63]
	ds_read2_b64 v[136:139], v153 offset0:12 offset1:14
	v_mfma_f32_32x32x16_bf16 v[96:111], v[140:143], v[128:131], v[96:111]
	s_waitcnt lgkmcnt(2)
	v_mfma_f32_32x32x16_bf16 v[16:31], v[248:251], v[148:151], v[16:31]
	ds_read2_b64 v[140:143], v154 offset0:44 offset1:46
	v_mfma_f32_32x32x16_bf16 v[80:95], v[248:251], v[128:131], v[80:95]
	s_waitcnt lgkmcnt(2)
	v_mfma_f32_32x32x16_bf16 v[0:15], v[252:255], v[148:151], v[0:15]
	ds_read2_b64 v[248:251], v155 offset0:76 offset1:78
	v_mfma_f32_32x32x16_bf16 v[32:47], v[252:255], v[128:131], v[32:47]
	s_waitcnt lgkmcnt(2)
	v_mfma_f32_32x32x16_bf16 v[64:79], v[136:139], v[144:147], v[64:79]
	ds_read2_b64 v[252:255], v156 offset0:108 offset1:110
	v_mfma_f32_32x32x16_bf16 v[112:127], v[136:139], v[132:135], v[112:127]
	s_waitcnt lgkmcnt(2)
	v_mfma_f32_32x32x16_bf16 v[48:63], v[140:143], v[144:147], v[48:63]
	v_mfma_f32_32x32x16_bf16 v[96:111], v[140:143], v[132:135], v[96:111]
	s_waitcnt lgkmcnt(1)
	v_mfma_f32_32x32x16_bf16 v[16:31], v[248:251], v[144:147], v[16:31]
	v_mfma_f32_32x32x16_bf16 v[80:95], v[248:251], v[132:135], v[80:95]
	s_waitcnt lgkmcnt(0)
	v_mfma_f32_32x32x16_bf16 v[0:15], v[252:255], v[144:147], v[0:15]
	v_mfma_f32_32x32x16_bf16 v[32:47], v[252:255], v[132:135], v[32:47]
	s_setprio 0
